# grid barrier: waiting XCD leaders poll the cross-XCD arrival counter directly; per-XCD release add dropped (no pollers left)
# baseline (speedup 1.0000x reference)
;   DI unsigned* bar() const { return (unsigned*)(ws + OFF_BAR); }
; __device__ __forceinline__ unsigned xb_ld(unsigned* p)              { return __hip_atomic_load(p, __ATOMIC_RELAXED, __HIP_MEMORY_SCOPE_AGENT); }
; __device__ __forceinline__ unsigned xb_add(unsigned* p, unsigned v) { return __hip_atomic_fetch_add(p, v, __ATOMIC_RELAXED, __HIP_MEMORY_SCOPE_AGENT); }
; #define XB_SPIN(cond, bar) do { unsigned _sp = 0; while (cond) { __builtin_amdgcn_s_sleep(1); \
;     if ((++_sp & 255u) == 0u) { if (xb_ld(&(bar)[XB_TMO])) break; if (_sp > XB_SPIN_CAP) { atomicAdd(&(bar)[XB_TMO], 1u); break; } } } } while (0)
; __device__ __forceinline__ void xcd_barrier(const XcdBarrier& b) {
;     ...
;             const unsigned og = xb_add(&bar[XB_TOP], 1u);
;             const unsigned tg = og / nx;
;             if (og + 1u == (tg + 1u) * nx) xb_add(&bar[XB_TOPGEN], 1u);
;             else XB_SPIN(xb_ld(&bar[XB_TOPGEN]) == tg, bar);
.Lgs_168:
	s_or_b64 exec, exec, s[6:7]
	v_cvt_f32_u32_e32 v3, v1
	s_waitcnt vmcnt(0)
	v_readfirstlane_b32 s4, v2
	s_add_u32 s6, s22, 0x1e6c4500
	s_addc_u32 s7, s23, 0
	s_add_u32 s98, s22, 0x1e6c4400
	s_addc_u32 s99, s23, 0
	v_rcp_iflag_f32_e32 v3, v3
	v_add_u32_e32 v0, s4, v0
	v_add_u32_e32 v4, 1, v0
	s_mov_b64 s[8:9], -1
	v_mul_f32_e32 v2, 0x4f7ffffe, v3
	v_cvt_u32_f32_e32 v2, v2
	v_sub_u32_e32 v3, 0, v1
	v_mul_lo_u32 v3, v3, v2
	v_mul_hi_u32 v3, v2, v3
	v_add_u32_e32 v2, v2, v3
	v_mul_hi_u32 v2, v0, v2
	v_mul_lo_u32 v3, v2, v1
	v_sub_u32_e32 v0, v0, v3
	v_add_u32_e32 v5, 1, v2
	v_cmp_ge_u32_e32 vcc, v0, v1
	v_sub_u32_e32 v3, v0, v1
	s_nop 0
	v_cndmask_b32_e32 v2, v2, v5, vcc
	v_cndmask_b32_e32 v0, v0, v3, vcc
	v_add_u32_e32 v3, 1, v2
	v_cmp_ge_u32_e32 vcc, v0, v1
	s_nop 1
	v_cndmask_b32_e32 v2, v2, v3, vcc
	v_mul_lo_u32 v0, v1, v2
	v_add_u32_e32 v0, v0, v1
	v_cmp_ne_u32_e32 vcc, v4, v0
	v_mov_b32_e32 v6, v0
	v_mov_b64_e32 v[0:1], s[6:7]
	s_and_saveexec_b64 s[4:5], vcc
	s_cbranch_execz .Lgs_180
	v_mov_b32_e32 v0, 0
	global_load_dword v1, v0, s[98:99] sc1
	s_mov_b64 s[12:13], 0
	s_waitcnt vmcnt(0)
	v_cmp_lt_u32_e32 vcc, v1, v6
	s_and_saveexec_b64 s[10:11], vcc
	s_cbranch_execz .Lgs_179
	s_add_u32 s8, s22, 0x1e6c1200
	s_addc_u32 s9, s23, 0
	s_mov_b32 s26, 1
	s_branch .Lgs_172

;   DI unsigned* bar() const { return (unsigned*)(ws + OFF_BAR); }
; __device__ __forceinline__ unsigned xb_ld(unsigned* p)              { return __hip_atomic_load(p, __ATOMIC_RELAXED, __HIP_MEMORY_SCOPE_AGENT); }
; __device__ __forceinline__ unsigned xb_add(unsigned* p, unsigned v) { return __hip_atomic_fetch_add(p, v, __ATOMIC_RELAXED, __HIP_MEMORY_SCOPE_AGENT); }
; #define XB_SPIN(cond, bar) do { unsigned _sp = 0; while (cond) { __builtin_amdgcn_s_sleep(1); \
;     if ((++_sp & 255u) == 0u) { if (xb_ld(&(bar)[XB_TMO])) break; if (_sp > XB_SPIN_CAP) { atomicAdd(&(bar)[XB_TMO], 1u); break; } } } } while (0)
; __device__ __forceinline__ void xcd_barrier(const XcdBarrier& b) {
;     ...
;             const unsigned og = xb_add(&bar[XB_TOP], 1u);
;             const unsigned tg = og / nx;
;             if (og + 1u == (tg + 1u) * nx) xb_add(&bar[XB_TOPGEN], 1u);
;             else XB_SPIN(xb_ld(&bar[XB_TOPGEN]) == tg, bar);
.LBB0_660:
	s_or_b64 exec, exec, s[8:9]
	v_cvt_f32_u32_e32 v3, v1
	s_waitcnt vmcnt(0)
	v_readfirstlane_b32 s4, v2
	s_add_u32 s8, s22, 0x1e6c4500
	s_addc_u32 s9, s23, 0
	s_add_u32 s98, s22, 0x1e6c4400
	s_addc_u32 s99, s23, 0
	v_rcp_iflag_f32_e32 v3, v3
	v_add_u32_e32 v0, s4, v0
	v_add_u32_e32 v4, 1, v0
	s_mov_b64 s[10:11], -1
	v_mul_f32_e32 v2, 0x4f7ffffe, v3
	v_cvt_u32_f32_e32 v2, v2
	v_sub_u32_e32 v3, 0, v1
	v_mul_lo_u32 v3, v3, v2
	v_mul_hi_u32 v3, v2, v3
	v_add_u32_e32 v2, v2, v3
	v_mul_hi_u32 v2, v0, v2
	v_mul_lo_u32 v3, v2, v1
	v_sub_u32_e32 v0, v0, v3
	v_add_u32_e32 v5, 1, v2
	v_cmp_ge_u32_e32 vcc, v0, v1
	v_sub_u32_e32 v3, v0, v1
	s_nop 0
	v_cndmask_b32_e32 v2, v2, v5, vcc
	v_cndmask_b32_e32 v0, v0, v3, vcc
	v_add_u32_e32 v3, 1, v2
	v_cmp_ge_u32_e32 vcc, v0, v1
	s_nop 1
	v_cndmask_b32_e32 v2, v2, v3, vcc
	v_mul_lo_u32 v0, v1, v2
	v_add_u32_e32 v0, v0, v1
	v_cmp_ne_u32_e32 vcc, v4, v0
	v_mov_b32_e32 v6, v0
	v_mov_b64_e32 v[0:1], s[8:9]
	s_and_saveexec_b64 s[4:5], vcc
	s_cbranch_execz .LBB0_672
	v_mov_b32_e32 v0, 0
	global_load_dword v1, v0, s[98:99] sc1
	s_mov_b64 s[14:15], 0
	s_waitcnt vmcnt(0)
	v_cmp_lt_u32_e32 vcc, v1, v6
	s_and_saveexec_b64 s[12:13], vcc
	s_cbranch_execz .LBB0_671
	s_add_u32 s10, s22, 0x1e6c1200
	s_addc_u32 s11, s23, 0
	s_mov_b32 s28, 1
	s_branch .LBB0_664

;   DI unsigned* bar() const { return (unsigned*)(ws + OFF_BAR); }
; __device__ __forceinline__ unsigned xb_ld(unsigned* p)              { return __hip_atomic_load(p, __ATOMIC_RELAXED, __HIP_MEMORY_SCOPE_AGENT); }
; __device__ __forceinline__ unsigned xb_add(unsigned* p, unsigned v) { return __hip_atomic_fetch_add(p, v, __ATOMIC_RELAXED, __HIP_MEMORY_SCOPE_AGENT); }
; #define XB_SPIN(cond, bar) do { unsigned _sp = 0; while (cond) { __builtin_amdgcn_s_sleep(1); \
;     if ((++_sp & 255u) == 0u) { if (xb_ld(&(bar)[XB_TMO])) break; if (_sp > XB_SPIN_CAP) { atomicAdd(&(bar)[XB_TMO], 1u); break; } } } } while (0)
; __device__ __forceinline__ void xcd_barrier(const XcdBarrier& b) {
;     ...
;             const unsigned og = xb_add(&bar[XB_TOP], 1u);
;             const unsigned tg = og / nx;
;             if (og + 1u == (tg + 1u) * nx) xb_add(&bar[XB_TOPGEN], 1u);
;             else XB_SPIN(xb_ld(&bar[XB_TOPGEN]) == tg, bar);
.LBB0_802:
	s_or_b64 exec, exec, s[8:9]
	v_cvt_f32_u32_e32 v3, v1
	s_waitcnt vmcnt(0)
	v_readfirstlane_b32 s6, v2
	s_add_u32 s8, s22, 0x1e6c4500
	s_addc_u32 s9, s23, 0
	s_add_u32 s98, s22, 0x1e6c4400
	s_addc_u32 s99, s23, 0
	v_rcp_iflag_f32_e32 v3, v3
	v_add_u32_e32 v0, s6, v0
	v_add_u32_e32 v4, 1, v0
	s_mov_b64 s[10:11], -1
	v_mul_f32_e32 v2, 0x4f7ffffe, v3
	v_cvt_u32_f32_e32 v2, v2
	v_sub_u32_e32 v3, 0, v1
	v_mul_lo_u32 v3, v3, v2
	v_mul_hi_u32 v3, v2, v3
	v_add_u32_e32 v2, v2, v3
	v_mul_hi_u32 v2, v0, v2
	v_mul_lo_u32 v3, v2, v1
	v_sub_u32_e32 v0, v0, v3
	v_add_u32_e32 v5, 1, v2
	v_cmp_ge_u32_e32 vcc, v0, v1
	v_sub_u32_e32 v3, v0, v1
	s_nop 0
	v_cndmask_b32_e32 v2, v2, v5, vcc
	v_cndmask_b32_e32 v0, v0, v3, vcc
	v_add_u32_e32 v3, 1, v2
	v_cmp_ge_u32_e32 vcc, v0, v1
	s_nop 1
	v_cndmask_b32_e32 v2, v2, v3, vcc
	v_mul_lo_u32 v0, v1, v2
	v_add_u32_e32 v0, v0, v1
	v_cmp_ne_u32_e32 vcc, v4, v0
	v_mov_b32_e32 v6, v0
	v_mov_b64_e32 v[0:1], s[8:9]
	s_and_saveexec_b64 s[6:7], vcc
	s_cbranch_execz .LBB0_814
	v_mov_b32_e32 v0, 0
	global_load_dword v1, v0, s[98:99] sc1
	s_mov_b64 s[14:15], 0
	s_waitcnt vmcnt(0)
	v_cmp_lt_u32_e32 vcc, v1, v6
	s_and_saveexec_b64 s[12:13], vcc
	s_cbranch_execz .LBB0_813
	s_add_u32 s10, s22, 0x1e6c1200
	s_addc_u32 s11, s23, 0
	s_mov_b32 s28, 1
	s_branch .LBB0_806

;   DI unsigned* bar() const { return (unsigned*)(ws + OFF_BAR); }
; __device__ __forceinline__ unsigned xb_ld(unsigned* p)              { return __hip_atomic_load(p, __ATOMIC_RELAXED, __HIP_MEMORY_SCOPE_AGENT); }
; __device__ __forceinline__ unsigned xb_add(unsigned* p, unsigned v) { return __hip_atomic_fetch_add(p, v, __ATOMIC_RELAXED, __HIP_MEMORY_SCOPE_AGENT); }
; #define XB_SPIN(cond, bar) do { unsigned _sp = 0; while (cond) { __builtin_amdgcn_s_sleep(1); \
;     if ((++_sp & 255u) == 0u) { if (xb_ld(&(bar)[XB_TMO])) break; if (_sp > XB_SPIN_CAP) { atomicAdd(&(bar)[XB_TMO], 1u); break; } } } } while (0)
; __device__ __forceinline__ void xcd_barrier(const XcdBarrier& b) {
;     ...
;             const unsigned og = xb_add(&bar[XB_TOP], 1u);
;             const unsigned tg = og / nx;
;             if (og + 1u == (tg + 1u) * nx) xb_add(&bar[XB_TOPGEN], 1u);
;             else XB_SPIN(xb_ld(&bar[XB_TOPGEN]) == tg, bar);
.LBB0_857:
	s_or_b64 exec, exec, s[8:9]
	v_cvt_f32_u32_e32 v3, v1
	s_waitcnt vmcnt(0)
	v_readfirstlane_b32 s6, v2
	s_add_u32 s8, s22, 0x1e6c4500
	s_addc_u32 s9, s23, 0
	s_add_u32 s98, s22, 0x1e6c4400
	s_addc_u32 s99, s23, 0
	v_rcp_iflag_f32_e32 v3, v3
	v_add_u32_e32 v0, s6, v0
	v_add_u32_e32 v4, 1, v0
	s_mov_b64 s[10:11], -1
	v_mul_f32_e32 v2, 0x4f7ffffe, v3
	v_cvt_u32_f32_e32 v2, v2
	v_sub_u32_e32 v3, 0, v1
	v_mul_lo_u32 v3, v3, v2
	v_mul_hi_u32 v3, v2, v3
	v_add_u32_e32 v2, v2, v3
	v_mul_hi_u32 v2, v0, v2
	v_mul_lo_u32 v3, v2, v1
	v_sub_u32_e32 v0, v0, v3
	v_add_u32_e32 v5, 1, v2
	v_cmp_ge_u32_e32 vcc, v0, v1
	v_sub_u32_e32 v3, v0, v1
	s_nop 0
	v_cndmask_b32_e32 v2, v2, v5, vcc
	v_cndmask_b32_e32 v0, v0, v3, vcc
	v_add_u32_e32 v3, 1, v2
	v_cmp_ge_u32_e32 vcc, v0, v1
	s_nop 1
	v_cndmask_b32_e32 v2, v2, v3, vcc
	v_mul_lo_u32 v0, v1, v2
	v_add_u32_e32 v0, v0, v1
	v_cmp_ne_u32_e32 vcc, v4, v0
	v_mov_b32_e32 v6, v0
	v_mov_b64_e32 v[0:1], s[8:9]
	s_and_saveexec_b64 s[6:7], vcc
	s_cbranch_execz .LBB0_869
	v_mov_b32_e32 v0, 0
	global_load_dword v1, v0, s[98:99] sc1
	s_mov_b64 s[14:15], 0
	s_waitcnt vmcnt(0)
	v_cmp_lt_u32_e32 vcc, v1, v6
	s_and_saveexec_b64 s[12:13], vcc
	s_cbranch_execz .LBB0_868
	s_add_u32 s10, s22, 0x1e6c1200
	s_addc_u32 s11, s23, 0
	s_mov_b32 s27, 1
	s_branch .LBB0_861

;   DI unsigned* bar() const { return (unsigned*)(ws + OFF_BAR); }
; __device__ __forceinline__ unsigned xb_ld(unsigned* p)              { return __hip_atomic_load(p, __ATOMIC_RELAXED, __HIP_MEMORY_SCOPE_AGENT); }
; __device__ __forceinline__ unsigned xb_add(unsigned* p, unsigned v) { return __hip_atomic_fetch_add(p, v, __ATOMIC_RELAXED, __HIP_MEMORY_SCOPE_AGENT); }
; #define XB_SPIN(cond, bar) do { unsigned _sp = 0; while (cond) { __builtin_amdgcn_s_sleep(1); \
;     if ((++_sp & 255u) == 0u) { if (xb_ld(&(bar)[XB_TMO])) break; if (_sp > XB_SPIN_CAP) { atomicAdd(&(bar)[XB_TMO], 1u); break; } } } } while (0)
; __device__ __forceinline__ void xcd_barrier(const XcdBarrier& b) {
;     ...
;             const unsigned og = xb_add(&bar[XB_TOP], 1u);
;             const unsigned tg = og / nx;
;             if (og + 1u == (tg + 1u) * nx) xb_add(&bar[XB_TOPGEN], 1u);
;             else XB_SPIN(xb_ld(&bar[XB_TOPGEN]) == tg, bar);
.LBB0_1690:
	s_or_b64 exec, exec, s[6:7]
	v_cvt_f32_u32_e32 v3, v1
	s_waitcnt vmcnt(0)
	v_readfirstlane_b32 s4, v2
	s_add_u32 s6, s22, 0x1e6c4500
	s_addc_u32 s7, s23, 0
	s_add_u32 s98, s22, 0x1e6c4400
	s_addc_u32 s99, s23, 0
	v_rcp_iflag_f32_e32 v3, v3
	v_add_u32_e32 v0, s4, v0
	v_add_u32_e32 v4, 1, v0
	s_mov_b64 s[8:9], -1
	v_mul_f32_e32 v2, 0x4f7ffffe, v3
	v_cvt_u32_f32_e32 v2, v2
	v_sub_u32_e32 v3, 0, v1
	v_mul_lo_u32 v3, v3, v2
	v_mul_hi_u32 v3, v2, v3
	v_add_u32_e32 v2, v2, v3
	v_mul_hi_u32 v2, v0, v2
	v_mul_lo_u32 v3, v2, v1
	v_sub_u32_e32 v0, v0, v3
	v_add_u32_e32 v5, 1, v2
	v_cmp_ge_u32_e32 vcc, v0, v1
	v_sub_u32_e32 v3, v0, v1
	s_nop 0
	v_cndmask_b32_e32 v2, v2, v5, vcc
	v_cndmask_b32_e32 v0, v0, v3, vcc
	v_add_u32_e32 v3, 1, v2
	v_cmp_ge_u32_e32 vcc, v0, v1
	s_nop 1
	v_cndmask_b32_e32 v2, v2, v3, vcc
	v_mul_lo_u32 v0, v1, v2
	v_add_u32_e32 v0, v0, v1
	v_cmp_ne_u32_e32 vcc, v4, v0
	v_mov_b32_e32 v6, v0
	v_mov_b64_e32 v[0:1], s[6:7]
	s_and_saveexec_b64 s[4:5], vcc
	s_cbranch_execz .LBB0_1702
	v_mov_b32_e32 v0, 0
	global_load_dword v1, v0, s[98:99] sc1
	s_mov_b64 s[12:13], 0
	s_waitcnt vmcnt(0)
	v_cmp_lt_u32_e32 vcc, v1, v6
	s_and_saveexec_b64 s[10:11], vcc
	s_cbranch_execz .LBB0_1701
	s_add_u32 s8, s22, 0x1e6c1200
	s_addc_u32 s9, s23, 0
	s_mov_b32 s24, 1
	s_branch .LBB0_1694
